# P5 HFF stores with nt cache policy (on top of nt output stores)
# baseline (speedup 1.0000x reference)
.LBB0_1140:
	s_or_b64 exec, exec, s[26:27]
	global_store_dwordx4 v[126:127], v[116:119], off nt
	global_store_dwordx4 v[124:125], v[120:123], off nt
	ds_read_b32 v116, v143 offset:64
	v_max_f32_e32 v112, 0, v112
	v_max_f32_e32 v113, 0, v113
	v_max_f32_e32 v114, 0, v114
	v_max_f32_e32 v115, 0, v115
	v_max_f32_e32 v104, 0, v104
	v_max_f32_e32 v100, 0, v100
	v_max_f32_e32 v105, 0, v105
	v_max_f32_e32 v106, 0, v106
	v_max_f32_e32 v108, 0, v108
	v_mul_f32_e32 v112, v112, v112
	v_max_f32_e32 v109, 0, v109
	v_mul_f32_e32 v113, v113, v113
	v_max_f32_e32 v110, 0, v110
	v_mul_f32_e32 v114, v114, v114
	v_max_f32_e32 v111, 0, v111
	v_mul_f32_e32 v115, v115, v115
	v_mul_f32_e32 v104, v104, v104
	v_mul_f32_e32 v100, v100, v100
	v_max_f32_e32 v101, 0, v101
	v_mul_f32_e32 v105, v105, v105
	v_mul_f32_e32 v106, v106, v106
	v_max_f32_e32 v107, 0, v107
	s_waitcnt lgkmcnt(0)
	v_mul_f32_e32 v112, v112, v116
	v_mul_f32_e32 v108, v108, v108
	v_mul_f32_e32 v113, v113, v116
	v_mul_f32_e32 v109, v109, v109
	v_mul_f32_e32 v114, v114, v116
	v_mul_f32_e32 v110, v110, v110
	v_mul_f32_e32 v115, v115, v116
	v_mul_f32_e32 v111, v111, v111
	v_mul_f32_e32 v104, v104, v116
	v_mul_f32_e32 v100, v100, v116
	v_mul_f32_e32 v105, v105, v116
	v_mul_f32_e32 v101, v101, v101
	v_mul_f32_e32 v106, v106, v116
	v_mul_f32_e32 v107, v107, v107
	v_mul_f32_e32 v108, v108, v116
	v_mul_f32_e32 v109, v109, v116
	v_mul_f32_e32 v110, v110, v116
	v_mul_f32_e32 v111, v111, v116
	v_cvt_pk_bf16_f32 v112, v112, v113
	v_cvt_pk_bf16_f32 v113, v114, v115
	v_cvt_pk_bf16_f32 v114, v108, v109
	v_cvt_pk_bf16_f32 v115, v110, v111
	v_mul_f32_e32 v101, v101, v116
	v_mul_f32_e32 v107, v107, v116
	v_cvt_pk_bf16_f32 v104, v104, v105
	v_cvt_pk_bf16_f32 v105, v106, v107
	v_cvt_pk_bf16_f32 v106, v100, v101
	v_or_b32_e32 v100, 16, v140
	v_max_f32_e32 v102, 0, v102
	v_max_f32_e32 v103, 0, v103
	v_ashrrev_i32_e32 v101, 31, v100
	v_mul_f32_e32 v102, v102, v102
	v_mul_f32_e32 v103, v103, v103
	v_lshlrev_b64 v[100:101], 13, v[100:101]
	v_mul_f32_e32 v102, v102, v116
	v_mul_f32_e32 v103, v103, v116
	v_lshl_add_u64 v[100:101], s[30:31], 0, v[100:101]
	v_cvt_pk_bf16_f32 v107, v102, v103
	v_lshl_add_u64 v[108:109], v[138:139], 1, v[100:101]
	v_mov_b32_e32 v100, 0
	v_mov_b32_e32 v101, 0
	v_mov_b32_e32 v102, 0
	v_mov_b32_e32 v103, 0
	v_mov_b32_dpp v100, v104 row_ror:8 row_mask:0xf bank_mask:0xf
	v_mov_b32_dpp v101, v105 row_ror:8 row_mask:0xf bank_mask:0xf
	v_mov_b32_dpp v102, v106 row_ror:8 row_mask:0xf bank_mask:0xf
	v_mov_b32_dpp v103, v107 row_ror:8 row_mask:0xf bank_mask:0xf
	v_lshl_add_u64 v[110:111], v[108:109], 0, s[46:47]
	v_mov_b32_e32 v104, v112
	v_mov_b32_e32 v105, v113
	v_mov_b32_e32 v106, v114
	v_mov_b32_e32 v107, v115
	s_and_saveexec_b64 s[26:27], s[4:5]
	s_cbranch_execz .LBB0_1142
	v_lshl_add_u64 v[116:117], v[108:109], 0, s[48:49]
	v_mov_b64_e32 v[110:111], v[108:109]
	v_mov_b32_e32 v104, v100
	v_mov_b32_e32 v105, v101
	v_mov_b32_e32 v106, v102
	v_mov_b32_e32 v107, v103
	v_mov_b32_e32 v100, v112
	v_mov_b32_e32 v101, v113
	v_mov_b32_e32 v102, v114
	v_mov_b32_e32 v103, v115
	v_mov_b64_e32 v[108:109], v[116:117]
.LBB0_1142:
	s_or_b64 exec, exec, s[26:27]
	global_store_dwordx4 v[110:111], v[100:103], off nt
	global_store_dwordx4 v[108:109], v[104:107], off nt
	ds_read_b32 v100, v143 offset:128
	v_max_f32_e32 v96, 0, v96
	v_max_f32_e32 v97, 0, v97
	v_max_f32_e32 v98, 0, v98
	v_max_f32_e32 v99, 0, v99
	v_max_f32_e32 v88, 0, v88
	v_max_f32_e32 v84, 0, v84
	v_max_f32_e32 v89, 0, v89
	v_max_f32_e32 v90, 0, v90
	v_max_f32_e32 v92, 0, v92
	v_mul_f32_e32 v96, v96, v96
	v_max_f32_e32 v93, 0, v93
	v_mul_f32_e32 v97, v97, v97
	v_max_f32_e32 v94, 0, v94
	v_mul_f32_e32 v98, v98, v98
	v_max_f32_e32 v95, 0, v95
	v_mul_f32_e32 v99, v99, v99
	v_mul_f32_e32 v88, v88, v88
	v_mul_f32_e32 v84, v84, v84
	v_max_f32_e32 v85, 0, v85
	v_mul_f32_e32 v89, v89, v89
	v_mul_f32_e32 v90, v90, v90
	v_max_f32_e32 v91, 0, v91
	s_waitcnt lgkmcnt(0)
	v_mul_f32_e32 v96, v96, v100
	v_mul_f32_e32 v92, v92, v92
	v_mul_f32_e32 v97, v97, v100
	v_mul_f32_e32 v93, v93, v93
	v_mul_f32_e32 v98, v98, v100
	v_mul_f32_e32 v94, v94, v94
	v_mul_f32_e32 v99, v99, v100
	v_mul_f32_e32 v95, v95, v95
	v_mul_f32_e32 v88, v88, v100
	v_mul_f32_e32 v84, v84, v100
	v_mul_f32_e32 v89, v89, v100
	v_mul_f32_e32 v85, v85, v85
	v_mul_f32_e32 v90, v90, v100
	v_mul_f32_e32 v91, v91, v91
	v_mul_f32_e32 v92, v92, v100
	v_mul_f32_e32 v93, v93, v100
	v_mul_f32_e32 v94, v94, v100
	v_mul_f32_e32 v95, v95, v100
	v_cvt_pk_bf16_f32 v96, v96, v97
	v_cvt_pk_bf16_f32 v97, v98, v99
	v_cvt_pk_bf16_f32 v98, v92, v93
	v_cvt_pk_bf16_f32 v99, v94, v95
	v_mul_f32_e32 v85, v85, v100
	v_mul_f32_e32 v91, v91, v100
	v_cvt_pk_bf16_f32 v88, v88, v89
	v_cvt_pk_bf16_f32 v89, v90, v91
	v_cvt_pk_bf16_f32 v90, v84, v85
	v_or_b32_e32 v84, 32, v140
	v_max_f32_e32 v86, 0, v86
	v_max_f32_e32 v87, 0, v87
	v_ashrrev_i32_e32 v85, 31, v84
	v_mul_f32_e32 v86, v86, v86
	v_mul_f32_e32 v87, v87, v87
	v_lshlrev_b64 v[84:85], 13, v[84:85]
	v_mul_f32_e32 v86, v86, v100
	v_mul_f32_e32 v87, v87, v100
	v_lshl_add_u64 v[84:85], s[30:31], 0, v[84:85]
	v_cvt_pk_bf16_f32 v91, v86, v87
	v_lshl_add_u64 v[92:93], v[138:139], 1, v[84:85]
	v_mov_b32_e32 v84, 0
	v_mov_b32_e32 v85, 0
	v_mov_b32_e32 v86, 0
	v_mov_b32_e32 v87, 0
	v_mov_b32_dpp v84, v88 row_ror:8 row_mask:0xf bank_mask:0xf
	v_mov_b32_dpp v85, v89 row_ror:8 row_mask:0xf bank_mask:0xf
	v_mov_b32_dpp v86, v90 row_ror:8 row_mask:0xf bank_mask:0xf
	v_mov_b32_dpp v87, v91 row_ror:8 row_mask:0xf bank_mask:0xf
	v_lshl_add_u64 v[94:95], v[92:93], 0, s[46:47]
	v_mov_b32_e32 v88, v96
	v_mov_b32_e32 v89, v97
	v_mov_b32_e32 v90, v98
	v_mov_b32_e32 v91, v99
	s_and_saveexec_b64 s[26:27], s[4:5]
	s_cbranch_execz .LBB0_1144
	v_lshl_add_u64 v[100:101], v[92:93], 0, s[48:49]
	v_mov_b64_e32 v[94:95], v[92:93]
	v_mov_b32_e32 v88, v84
	v_mov_b32_e32 v89, v85
	v_mov_b32_e32 v90, v86
	v_mov_b32_e32 v91, v87
	v_mov_b32_e32 v84, v96
	v_mov_b32_e32 v85, v97
	v_mov_b32_e32 v86, v98
	v_mov_b32_e32 v87, v99
	v_mov_b64_e32 v[92:93], v[100:101]
.LBB0_1144:
	s_or_b64 exec, exec, s[26:27]
	global_store_dwordx4 v[94:95], v[84:87], off nt
	global_store_dwordx4 v[92:93], v[88:91], off nt
	ds_read_b32 v84, v143 offset:192
	v_max_f32_e32 v80, 0, v80
	v_max_f32_e32 v81, 0, v81
	v_max_f32_e32 v82, 0, v82
	v_max_f32_e32 v83, 0, v83
	v_max_f32_e32 v72, 0, v72
	v_max_f32_e32 v68, 0, v68
	v_max_f32_e32 v73, 0, v73
	v_max_f32_e32 v74, 0, v74
	v_max_f32_e32 v76, 0, v76
	v_mul_f32_e32 v80, v80, v80
	v_max_f32_e32 v77, 0, v77
	v_mul_f32_e32 v81, v81, v81
	v_max_f32_e32 v78, 0, v78
	v_mul_f32_e32 v82, v82, v82
	v_max_f32_e32 v79, 0, v79
	v_mul_f32_e32 v83, v83, v83
	v_mul_f32_e32 v72, v72, v72
	v_mul_f32_e32 v68, v68, v68
	v_max_f32_e32 v69, 0, v69
	v_mul_f32_e32 v73, v73, v73
	v_mul_f32_e32 v74, v74, v74
	v_max_f32_e32 v75, 0, v75
	s_waitcnt lgkmcnt(0)
	v_mul_f32_e32 v80, v80, v84
	v_mul_f32_e32 v76, v76, v76
	v_mul_f32_e32 v81, v81, v84
	v_mul_f32_e32 v77, v77, v77
	v_mul_f32_e32 v82, v82, v84
	v_mul_f32_e32 v78, v78, v78
	v_mul_f32_e32 v83, v83, v84
	v_mul_f32_e32 v79, v79, v79
	v_mul_f32_e32 v72, v72, v84
	v_mul_f32_e32 v68, v68, v84
	v_mul_f32_e32 v73, v73, v84
	v_mul_f32_e32 v69, v69, v69
	v_mul_f32_e32 v74, v74, v84
	v_mul_f32_e32 v75, v75, v75
	v_mul_f32_e32 v76, v76, v84
	v_mul_f32_e32 v77, v77, v84
	v_mul_f32_e32 v78, v78, v84
	v_mul_f32_e32 v79, v79, v84
	v_cvt_pk_bf16_f32 v80, v80, v81
	v_cvt_pk_bf16_f32 v81, v82, v83
	v_cvt_pk_bf16_f32 v82, v76, v77
	v_cvt_pk_bf16_f32 v83, v78, v79
	v_mul_f32_e32 v69, v69, v84
	v_mul_f32_e32 v75, v75, v84
	v_cvt_pk_bf16_f32 v72, v72, v73
	v_cvt_pk_bf16_f32 v73, v74, v75
	v_cvt_pk_bf16_f32 v74, v68, v69
	v_or_b32_e32 v68, 48, v140
	v_max_f32_e32 v70, 0, v70
	v_max_f32_e32 v71, 0, v71
	v_ashrrev_i32_e32 v69, 31, v68
	v_mul_f32_e32 v70, v70, v70
	v_mul_f32_e32 v71, v71, v71
	v_lshlrev_b64 v[68:69], 13, v[68:69]
	v_mul_f32_e32 v70, v70, v84
	v_mul_f32_e32 v71, v71, v84
	v_lshl_add_u64 v[68:69], s[30:31], 0, v[68:69]
	v_cvt_pk_bf16_f32 v75, v70, v71
	v_lshl_add_u64 v[76:77], v[138:139], 1, v[68:69]
	v_mov_b32_e32 v68, 0
	v_mov_b32_e32 v69, 0
	v_mov_b32_e32 v70, 0
	v_mov_b32_e32 v71, 0
	v_mov_b32_dpp v68, v72 row_ror:8 row_mask:0xf bank_mask:0xf
	v_mov_b32_dpp v69, v73 row_ror:8 row_mask:0xf bank_mask:0xf
	v_mov_b32_dpp v70, v74 row_ror:8 row_mask:0xf bank_mask:0xf
	v_mov_b32_dpp v71, v75 row_ror:8 row_mask:0xf bank_mask:0xf
	v_lshl_add_u64 v[78:79], v[76:77], 0, s[46:47]
	v_mov_b32_e32 v72, v80
	v_mov_b32_e32 v73, v81
	v_mov_b32_e32 v74, v82
	v_mov_b32_e32 v75, v83
	s_and_saveexec_b64 s[26:27], s[4:5]
	s_cbranch_execz .LBB0_1146
	v_lshl_add_u64 v[84:85], v[76:77], 0, s[48:49]
	v_mov_b64_e32 v[78:79], v[76:77]
	v_mov_b32_e32 v72, v68
	v_mov_b32_e32 v73, v69
	v_mov_b32_e32 v74, v70
	v_mov_b32_e32 v75, v71
	v_mov_b32_e32 v68, v80
	v_mov_b32_e32 v69, v81
	v_mov_b32_e32 v70, v82
	v_mov_b32_e32 v71, v83
	v_mov_b64_e32 v[76:77], v[84:85]
.LBB0_1146:
	s_or_b64 exec, exec, s[26:27]
	global_store_dwordx4 v[78:79], v[68:71], off nt
	global_store_dwordx4 v[76:77], v[72:75], off nt
	ds_read_b32 v70, v143 offset:512
	v_max_f32_e32 v66, 0, v66
	v_mul_f32_e32 v66, v66, v66
	s_waitcnt lgkmcnt(0)
	v_mul_f32_e32 v68, v66, v70
	v_max_f32_e32 v66, v67, v67
	v_max_f32_e32 v66, 0, v66
	v_max_f32_e32 v56, 0, v56
	v_max_f32_e32 v52, 0, v52
	v_max_f32_e32 v57, 0, v57
	v_max_f32_e32 v53, 0, v53
	v_max_f32_e32 v58, 0, v58
	v_max_f32_e32 v64, 0, v64
	v_max_f32_e32 v60, 0, v60
	v_max_f32_e32 v65, 0, v65
	v_max_f32_e32 v61, 0, v61
	v_max_f32_e32 v62, 0, v62
	v_max_f32_e32 v63, 0, v63
	v_mul_f32_e32 v66, v66, v66
	v_mul_f32_e32 v56, v56, v56
	v_mul_f32_e32 v52, v52, v52
	v_mul_f32_e32 v57, v57, v57
	v_mul_f32_e32 v53, v53, v53
	v_mul_f32_e32 v58, v58, v58
	v_max_f32_e32 v59, 0, v59
	v_mul_f32_e32 v64, v64, v64
	v_mul_f32_e32 v60, v60, v60
	v_mul_f32_e32 v65, v65, v65
	v_mul_f32_e32 v61, v61, v61
	v_mul_f32_e32 v62, v62, v62
	v_mul_f32_e32 v67, v66, v70
	v_mul_f32_e32 v63, v63, v63
	v_mul_f32_e32 v56, v56, v70
	v_mul_f32_e32 v52, v52, v70
	v_mul_f32_e32 v57, v57, v70
	v_mul_f32_e32 v53, v53, v70
	v_mul_f32_e32 v58, v58, v70
	v_mul_f32_e32 v59, v59, v59
	v_mul_f32_e32 v64, v64, v70
	v_mul_f32_e32 v60, v60, v70
	v_mul_f32_e32 v65, v65, v70
	v_mul_f32_e32 v61, v61, v70
	v_mul_f32_e32 v62, v62, v70
	v_mul_f32_e32 v63, v63, v70
	v_cvt_pk_bf16_f32 v66, v64, v65
	v_cvt_pk_bf16_f32 v67, v68, v67
	v_cvt_pk_bf16_f32 v68, v60, v61
	v_cvt_pk_bf16_f32 v69, v62, v63
	v_max_f32_e32 v54, 0, v54
	v_max_f32_e32 v55, 0, v55
	v_mul_f32_e32 v59, v59, v70
	v_cvt_pk_bf16_f32 v56, v56, v57
	v_cvt_pk_bf16_f32 v57, v58, v59
	v_cvt_pk_bf16_f32 v58, v52, v53
	v_lshlrev_b64 v[52:53], 13, v[140:141]
	v_mul_f32_e32 v54, v54, v54
	v_mul_f32_e32 v55, v55, v55
	v_lshl_add_u64 v[52:53], s[30:31], 0, v[52:53]
	v_mul_f32_e32 v54, v54, v70
	v_mul_f32_e32 v55, v55, v70
	v_lshl_add_u64 v[60:61], v[138:139], 1, v[52:53]
	s_mov_b64 s[26:27], 0x100000
	v_cvt_pk_bf16_f32 v59, v54, v55
	v_lshl_add_u64 v[62:63], v[60:61], 0, s[26:27]
	v_mov_b32_e32 v52, 0
	v_mov_b32_e32 v53, 0
	v_mov_b32_e32 v54, 0
	v_mov_b32_e32 v55, 0
	s_mov_b64 s[26:27], 0xf0040
	v_mov_b32_dpp v52, v56 row_ror:8 row_mask:0xf bank_mask:0xf
	v_mov_b32_dpp v53, v57 row_ror:8 row_mask:0xf bank_mask:0xf
	v_mov_b32_dpp v54, v58 row_ror:8 row_mask:0xf bank_mask:0xf
	v_mov_b32_dpp v55, v59 row_ror:8 row_mask:0xf bank_mask:0xf
	v_lshl_add_u64 v[64:65], v[60:61], 0, s[26:27]
	v_mov_b32_e32 v56, v66
	v_mov_b32_e32 v57, v67
	v_mov_b32_e32 v58, v68
	v_mov_b32_e32 v59, v69
	s_and_saveexec_b64 s[26:27], s[4:5]
	s_cbranch_execz .LBB0_1148
	v_lshl_add_u64 v[70:71], v[62:63], 0, s[48:49]
	v_mov_b64_e32 v[64:65], v[62:63]
	v_mov_b32_e32 v56, v52
	v_mov_b32_e32 v57, v53
	v_mov_b32_e32 v58, v54
	v_mov_b32_e32 v59, v55
	v_mov_b32_e32 v52, v66
	v_mov_b32_e32 v53, v67
	v_mov_b32_e32 v54, v68
	v_mov_b32_e32 v55, v69
	v_mov_b64_e32 v[62:63], v[70:71]
.LBB0_1148:
	s_or_b64 exec, exec, s[26:27]
	global_store_dwordx4 v[64:65], v[52:55], off nt
	global_store_dwordx4 v[62:63], v[56:59], off nt
	ds_read_b32 v52, v143 offset:576
	v_max_f32_e32 v48, 0, v48
	v_max_f32_e32 v44, 0, v44
	v_max_f32_e32 v49, 0, v49
	v_max_f32_e32 v45, 0, v45
	v_max_f32_e32 v50, 0, v50
	v_max_f32_e32 v51, 0, v51
	v_max_f32_e32 v40, 0, v40
	v_max_f32_e32 v36, 0, v36
	v_max_f32_e32 v41, 0, v41
	v_max_f32_e32 v37, 0, v37
	v_max_f32_e32 v42, 0, v42
	v_max_f32_e32 v38, 0, v38
	v_max_f32_e32 v43, 0, v43
	v_max_f32_e32 v39, 0, v39
	v_mul_f32_e32 v48, v48, v48
	v_mul_f32_e32 v44, v44, v44
	v_mul_f32_e32 v49, v49, v49
	v_mul_f32_e32 v45, v45, v45
	v_max_f32_e32 v46, 0, v46
	v_mul_f32_e32 v50, v50, v50
	v_max_f32_e32 v47, 0, v47
	v_mul_f32_e32 v51, v51, v51
	v_mul_f32_e32 v40, v40, v40
	v_mul_f32_e32 v36, v36, v36
	v_mul_f32_e32 v41, v41, v41
	v_mul_f32_e32 v37, v37, v37
	v_mul_f32_e32 v42, v42, v42
	v_mul_f32_e32 v38, v38, v38
	v_mul_f32_e32 v43, v43, v43
	v_mul_f32_e32 v39, v39, v39
	s_waitcnt lgkmcnt(0)
	v_mul_f32_e32 v48, v48, v52
	v_mul_f32_e32 v44, v44, v52
	v_mul_f32_e32 v49, v49, v52
	v_mul_f32_e32 v45, v45, v52
	v_mul_f32_e32 v50, v50, v52
	v_mul_f32_e32 v46, v46, v46
	v_mul_f32_e32 v51, v51, v52
	v_mul_f32_e32 v47, v47, v47
	v_mul_f32_e32 v40, v40, v52
	v_mul_f32_e32 v36, v36, v52
	v_mul_f32_e32 v41, v41, v52
	v_mul_f32_e32 v37, v37, v52
	v_mul_f32_e32 v42, v42, v52
	v_mul_f32_e32 v38, v38, v52
	v_mul_f32_e32 v43, v43, v52
	v_mul_f32_e32 v39, v39, v52
	s_mov_b64 s[26:27], 0x120000
	v_mul_f32_e32 v46, v46, v52
	v_mul_f32_e32 v47, v47, v52
	v_cvt_pk_bf16_f32 v48, v48, v49
	v_cvt_pk_bf16_f32 v49, v50, v51
	v_cvt_pk_bf16_f32 v50, v44, v45
	v_cvt_pk_bf16_f32 v51, v46, v47
	v_cvt_pk_bf16_f32 v40, v40, v41
	v_cvt_pk_bf16_f32 v41, v42, v43
	v_cvt_pk_bf16_f32 v42, v36, v37
	v_cvt_pk_bf16_f32 v43, v38, v39
	v_lshl_add_u64 v[44:45], v[60:61], 0, s[26:27]
	v_mov_b32_e32 v36, 0
	v_mov_b32_e32 v37, 0
	v_mov_b32_e32 v38, 0
	v_mov_b32_e32 v39, 0
	s_mov_b64 s[26:27], 0x110040
	v_mov_b32_dpp v36, v40 row_ror:8 row_mask:0xf bank_mask:0xf
	v_mov_b32_dpp v37, v41 row_ror:8 row_mask:0xf bank_mask:0xf
	v_mov_b32_dpp v38, v42 row_ror:8 row_mask:0xf bank_mask:0xf
	v_mov_b32_dpp v39, v43 row_ror:8 row_mask:0xf bank_mask:0xf
	v_lshl_add_u64 v[46:47], v[60:61], 0, s[26:27]
	v_mov_b32_e32 v40, v48
	v_mov_b32_e32 v41, v49
	v_mov_b32_e32 v42, v50
	v_mov_b32_e32 v43, v51
	s_and_saveexec_b64 s[26:27], s[4:5]
	s_cbranch_execz .LBB0_1150
	v_lshl_add_u64 v[52:53], v[44:45], 0, s[48:49]
	v_mov_b64_e32 v[46:47], v[44:45]
	v_mov_b32_e32 v40, v36
	v_mov_b32_e32 v41, v37
	v_mov_b32_e32 v42, v38
	v_mov_b32_e32 v43, v39
	v_mov_b32_e32 v36, v48
	v_mov_b32_e32 v37, v49
	v_mov_b32_e32 v38, v50
	v_mov_b32_e32 v39, v51
	v_mov_b64_e32 v[44:45], v[52:53]
.LBB0_1150:
	s_or_b64 exec, exec, s[26:27]
	global_store_dwordx4 v[46:47], v[36:39], off nt
	global_store_dwordx4 v[44:45], v[40:43], off nt
	ds_read_b32 v38, v143 offset:640
	v_max_f32_e32 v34, 0, v34
	v_mul_f32_e32 v34, v34, v34
	s_waitcnt lgkmcnt(0)
	v_mul_f32_e32 v36, v34, v38
	v_max_f32_e32 v34, v35, v35
	v_max_f32_e32 v34, 0, v34
	v_max_f32_e32 v24, 0, v24
	v_max_f32_e32 v20, 0, v20
	v_max_f32_e32 v25, 0, v25
	v_max_f32_e32 v21, 0, v21
	v_max_f32_e32 v26, 0, v26
	v_max_f32_e32 v32, 0, v32
	v_max_f32_e32 v28, 0, v28
	v_max_f32_e32 v33, 0, v33
	v_max_f32_e32 v29, 0, v29
	v_max_f32_e32 v30, 0, v30
	v_max_f32_e32 v31, 0, v31
	v_mul_f32_e32 v34, v34, v34
	v_mul_f32_e32 v24, v24, v24
	v_mul_f32_e32 v20, v20, v20
	v_mul_f32_e32 v25, v25, v25
	v_mul_f32_e32 v21, v21, v21
	v_mul_f32_e32 v26, v26, v26
	v_max_f32_e32 v27, 0, v27
	v_mul_f32_e32 v32, v32, v32
	v_mul_f32_e32 v28, v28, v28
	v_mul_f32_e32 v33, v33, v33
	v_mul_f32_e32 v29, v29, v29
	v_mul_f32_e32 v30, v30, v30
	v_mul_f32_e32 v35, v34, v38
	v_mul_f32_e32 v31, v31, v31
	v_mul_f32_e32 v24, v24, v38
	v_mul_f32_e32 v20, v20, v38
	v_mul_f32_e32 v25, v25, v38
	v_mul_f32_e32 v21, v21, v38
	v_max_f32_e32 v22, 0, v22
	v_mul_f32_e32 v26, v26, v38
	v_max_f32_e32 v23, 0, v23
	v_mul_f32_e32 v27, v27, v27
	v_mul_f32_e32 v32, v32, v38
	v_mul_f32_e32 v28, v28, v38
	v_mul_f32_e32 v33, v33, v38
	v_mul_f32_e32 v29, v29, v38
	v_mul_f32_e32 v30, v30, v38
	v_mul_f32_e32 v31, v31, v38
	v_cvt_pk_bf16_f32 v34, v32, v33
	v_cvt_pk_bf16_f32 v35, v36, v35
	v_cvt_pk_bf16_f32 v36, v28, v29
	v_cvt_pk_bf16_f32 v37, v30, v31
	v_mul_f32_e32 v22, v22, v22
	v_mul_f32_e32 v27, v27, v38
	v_mul_f32_e32 v23, v23, v23
	v_cvt_pk_bf16_f32 v24, v24, v25
	v_cvt_pk_bf16_f32 v25, v26, v27
	v_cvt_pk_bf16_f32 v26, v20, v21
	v_lshlrev_b64 v[20:21], 13, v[140:141]
	v_mul_f32_e32 v22, v22, v38
	v_mul_f32_e32 v23, v23, v38
	v_lshl_add_u64 v[20:21], s[30:31], 0, v[20:21]
	v_cvt_pk_bf16_f32 v27, v22, v23
	v_lshl_add_u64 v[28:29], v[138:139], 1, v[20:21]
	s_mov_b64 s[26:27], 0x140000
	v_mov_b32_e32 v20, 0
	v_mov_b32_e32 v21, 0
	v_mov_b32_e32 v22, 0
	v_mov_b32_e32 v23, 0
	v_lshl_add_u64 v[30:31], v[28:29], 0, s[26:27]
	v_mov_b32_dpp v20, v24 row_ror:8 row_mask:0xf bank_mask:0xf
	v_mov_b32_dpp v21, v25 row_ror:8 row_mask:0xf bank_mask:0xf
	v_mov_b32_dpp v22, v26 row_ror:8 row_mask:0xf bank_mask:0xf
	v_mov_b32_dpp v23, v27 row_ror:8 row_mask:0xf bank_mask:0xf
	v_lshl_add_u64 v[32:33], v[28:29], 0, s[50:51]
	v_mov_b32_e32 v24, v34
	v_mov_b32_e32 v25, v35
	v_mov_b32_e32 v26, v36
	v_mov_b32_e32 v27, v37
	s_and_saveexec_b64 s[26:27], s[4:5]
	s_cbranch_execz .LBB0_1152
	v_lshl_add_u64 v[38:39], v[30:31], 0, s[48:49]
	v_mov_b64_e32 v[32:33], v[30:31]
	v_mov_b32_e32 v24, v20
	v_mov_b32_e32 v25, v21
	v_mov_b32_e32 v26, v22
	v_mov_b32_e32 v27, v23
	v_mov_b32_e32 v20, v34
	v_mov_b32_e32 v21, v35
	v_mov_b32_e32 v22, v36
	v_mov_b32_e32 v23, v37
	v_mov_b64_e32 v[30:31], v[38:39]
.LBB0_1152:
	s_or_b64 exec, exec, s[26:27]
	global_store_dwordx4 v[32:33], v[20:23], off nt
	global_store_dwordx4 v[30:31], v[24:27], off nt
	ds_read_b32 v20, v143 offset:704
	v_max_f32_e32 v16, 0, v16
	v_max_f32_e32 v17, 0, v17
	v_max_f32_e32 v18, 0, v18
	v_max_f32_e32 v19, 0, v19
	v_max_f32_e32 v8, 0, v8
	v_max_f32_e32 v4, 0, v4
	v_max_f32_e32 v9, 0, v9
	v_max_f32_e32 v5, 0, v5
	v_max_f32_e32 v10, 0, v10
	v_max_f32_e32 v6, 0, v6
	v_max_f32_e32 v11, 0, v11
	v_max_f32_e32 v7, 0, v7
	v_max_f32_e32 v12, 0, v12
	v_mul_f32_e32 v16, v16, v16
	v_max_f32_e32 v13, 0, v13
	v_mul_f32_e32 v17, v17, v17
	v_max_f32_e32 v14, 0, v14
	v_mul_f32_e32 v18, v18, v18
	v_max_f32_e32 v15, 0, v15
	v_mul_f32_e32 v19, v19, v19
	v_mul_f32_e32 v8, v8, v8
	v_mul_f32_e32 v4, v4, v4
	v_mul_f32_e32 v9, v9, v9
	v_mul_f32_e32 v5, v5, v5
	v_mul_f32_e32 v10, v10, v10
	v_mul_f32_e32 v6, v6, v6
	v_mul_f32_e32 v11, v11, v11
	v_mul_f32_e32 v7, v7, v7
	s_waitcnt lgkmcnt(0)
	v_mul_f32_e32 v16, v16, v20
	v_mul_f32_e32 v12, v12, v12
	v_mul_f32_e32 v17, v17, v20
	v_mul_f32_e32 v13, v13, v13
	v_mul_f32_e32 v18, v18, v20
	v_mul_f32_e32 v14, v14, v14
	v_mul_f32_e32 v19, v19, v20
	v_mul_f32_e32 v15, v15, v15
	v_mul_f32_e32 v8, v8, v20
	v_mul_f32_e32 v4, v4, v20
	v_mul_f32_e32 v9, v9, v20
	v_mul_f32_e32 v5, v5, v20
	v_mul_f32_e32 v10, v10, v20
	v_mul_f32_e32 v6, v6, v20
	v_mul_f32_e32 v11, v11, v20
	v_mul_f32_e32 v7, v7, v20
	v_mul_f32_e32 v12, v12, v20
	v_mul_f32_e32 v13, v13, v20
	v_mul_f32_e32 v14, v14, v20
	v_mul_f32_e32 v15, v15, v20
	v_cvt_pk_bf16_f32 v16, v16, v17
	v_cvt_pk_bf16_f32 v17, v18, v19
	v_cvt_pk_bf16_f32 v18, v12, v13
	v_cvt_pk_bf16_f32 v19, v14, v15
	v_cvt_pk_bf16_f32 v8, v8, v9
	v_cvt_pk_bf16_f32 v9, v10, v11
	v_cvt_pk_bf16_f32 v10, v4, v5
	v_cvt_pk_bf16_f32 v11, v6, v7
	v_mov_b32_e32 v4, 0
	v_mov_b32_e32 v5, 0
	v_mov_b32_e32 v6, 0
	v_mov_b32_e32 v7, 0
	v_lshl_add_u64 v[12:13], v[28:29], 0, s[52:53]
	v_mov_b32_dpp v4, v8 row_ror:8 row_mask:0xf bank_mask:0xf
	v_mov_b32_dpp v5, v9 row_ror:8 row_mask:0xf bank_mask:0xf
	v_mov_b32_dpp v6, v10 row_ror:8 row_mask:0xf bank_mask:0xf
	v_mov_b32_dpp v7, v11 row_ror:8 row_mask:0xf bank_mask:0xf
	v_lshl_add_u64 v[14:15], v[28:29], 0, s[54:55]
	v_mov_b32_e32 v8, v16
	v_mov_b32_e32 v9, v17
	v_mov_b32_e32 v10, v18
	v_mov_b32_e32 v11, v19
	s_and_saveexec_b64 s[26:27], s[4:5]
	s_cbranch_execz .LBB0_1154
	v_lshl_add_u64 v[20:21], v[12:13], 0, s[48:49]
	v_mov_b64_e32 v[14:15], v[12:13]
	v_mov_b32_e32 v8, v4
	v_mov_b32_e32 v9, v5
	v_mov_b32_e32 v10, v6
	v_mov_b32_e32 v11, v7
	v_mov_b32_e32 v4, v16
	v_mov_b32_e32 v5, v17
	v_mov_b32_e32 v6, v18
	v_mov_b32_e32 v7, v19
	v_mov_b64_e32 v[12:13], v[20:21]
.LBB0_1154:
	s_or_b64 exec, exec, s[26:27]
	s_andn2_b64 vcc, exec, s[10:11]
	s_mov_b64 s[10:11], -1
	global_store_dwordx4 v[14:15], v[4:7], off nt
	global_store_dwordx4 v[12:13], v[8:11], off nt
	s_cbranch_vccnz .LBB0_1127
	s_andn2_b64 vcc, exec, s[20:21]
	s_cbranch_vccnz .LBB0_1126
	s_barrier
	s_branch .LBB0_1126
